# prep S1: gate/decay loads issued together (one round trip instead of four), on top of S2b + attention epilogue
# speedup vs baseline: 1.0261x; 1.0073x over previous
.LBB0_362:
	s_or_b64 exec, exec, s[2:3]
	v_mul_f32_e32 v0, 0xbfb8aa3b, v5
	v_exp_f32_e32 v1, v0
	v_mul_f32_e32 v0, 0xbfb8aa3b, v8
	v_exp_f32_e32 v10, v0
	v_mul_f32_e32 v0, 0xbfb8aa3b, v9
	v_exp_f32_e32 v11, v0
	v_mul_f32_e32 v0, 0xbfb8aa3b, v6
	v_exp_f32_e32 v14, v0
	v_mul_f32_e32 v0, 0xbfb8aa3b, v7
	v_pk_add_f32 v[10:11], v[10:11], 1.0 op_sel_hi:[1,0]
	v_exp_f32_e32 v15, v0
	v_div_scale_f32 v13, s[2:3], v11, v11, v9
	v_rcp_f32_e32 v54, v13
	v_mul_f32_e32 v0, 0xbfb8aa3b, v2
	v_exp_f32_e32 v52, v0
	v_mul_f32_e32 v0, 0xbfb8aa3b, v3
	v_fma_f32 v55, -v13, v54, 1.0
	v_fmac_f32_e32 v54, v55, v54
	v_div_scale_f32 v55, vcc, v9, v11, v9
	v_mul_f32_e32 v56, v55, v54
	v_fma_f32 v57, -v13, v56, v55
	v_fmac_f32_e32 v56, v57, v54
	v_fma_f32 v13, -v13, v56, v55
	v_div_fmas_f32 v13, v13, v54, v56
	v_div_fixup_f32 v9, v13, v11, v9
	v_div_scale_f32 v11, s[2:3], v10, v10, v8
	v_rcp_f32_e32 v13, v11
	v_exp_f32_e32 v53, v0
	v_mul_f32_e32 v0, 0xbfb8aa3b, v4
	v_exp_f32_e32 v0, v0
	v_fma_f32 v54, -v11, v13, 1.0
	v_fmac_f32_e32 v13, v54, v13
	v_div_scale_f32 v54, vcc, v8, v10, v8
	v_mul_f32_e32 v55, v54, v13
	v_fma_f32 v56, -v11, v55, v54
	v_fmac_f32_e32 v55, v56, v13
	v_fma_f32 v11, -v11, v55, v54
	v_div_fmas_f32 v11, v11, v13, v55
	v_div_fixup_f32 v8, v11, v10, v8
	v_add_u32_e32 v10, 0x8900, v12
	ds_write2_b32 v10, v8, v9 offset1:1
	v_pk_add_f32 v[8:9], v[14:15], 1.0 op_sel_hi:[1,0]
	v_pk_add_f32 v[0:1], v[0:1], 1.0 op_sel_hi:[1,0]
	v_div_scale_f32 v10, s[2:3], v9, v9, v7
	v_rcp_f32_e32 v11, v10
	s_nop 0
	v_fma_f32 v13, -v10, v11, 1.0
	v_fmac_f32_e32 v11, v13, v11
	v_div_scale_f32 v13, vcc, v7, v9, v7
	v_mul_f32_e32 v14, v13, v11
	v_fma_f32 v15, -v10, v14, v13
	v_fmac_f32_e32 v14, v15, v11
	v_fma_f32 v10, -v10, v14, v13
	v_div_fmas_f32 v10, v10, v11, v14
	v_div_fixup_f32 v7, v10, v9, v7
	v_div_scale_f32 v9, s[2:3], v8, v8, v6
	v_rcp_f32_e32 v10, v9
	s_nop 0
	v_fma_f32 v11, -v9, v10, 1.0
	v_fmac_f32_e32 v10, v11, v10
	v_div_scale_f32 v11, vcc, v6, v8, v6
	v_mul_f32_e32 v13, v11, v10
	v_fma_f32 v14, -v9, v13, v11
	v_fmac_f32_e32 v13, v14, v10
	v_fma_f32 v9, -v9, v13, v11
	v_div_fmas_f32 v9, v9, v10, v13
	v_div_fixup_f32 v6, v9, v8, v6
	v_add_u32_e32 v8, 0x8908, v12
	ds_write2_b32 v8, v6, v7 offset1:1
	v_pk_add_f32 v[6:7], v[52:53], 1.0 op_sel_hi:[1,0]
	s_nop 0
	v_div_scale_f32 v8, s[2:3], v7, v7, v3
	v_rcp_f32_e32 v9, v8
	s_nop 0
	v_fma_f32 v10, -v8, v9, 1.0
	v_fmac_f32_e32 v9, v10, v9
	v_div_scale_f32 v10, vcc, v3, v7, v3
	v_mul_f32_e32 v11, v10, v9
	v_fma_f32 v13, -v8, v11, v10
	v_fmac_f32_e32 v11, v13, v9
	v_fma_f32 v8, -v8, v11, v10
	v_div_fmas_f32 v8, v8, v9, v11
	v_div_fixup_f32 v3, v8, v7, v3
	v_div_scale_f32 v7, s[2:3], v6, v6, v2
	v_rcp_f32_e32 v8, v7
	s_nop 0
	v_fma_f32 v9, -v7, v8, 1.0
	v_fmac_f32_e32 v8, v9, v8
	v_div_scale_f32 v9, vcc, v2, v6, v2
	v_mul_f32_e32 v10, v9, v8
	v_fma_f32 v11, -v7, v10, v9
	v_fmac_f32_e32 v10, v11, v8
	v_fma_f32 v7, -v7, v10, v9
	v_div_fmas_f32 v7, v7, v8, v10
	v_div_fixup_f32 v2, v7, v6, v2
	v_add_u32_e32 v6, 0x8910, v12
	ds_write2_b32 v6, v2, v3 offset1:1
	v_div_scale_f32 v2, s[2:3], v1, v1, v5
	v_rcp_f32_e32 v3, v2
	s_nop 0
	v_fma_f32 v6, -v2, v3, 1.0
	v_fmac_f32_e32 v3, v6, v3
	v_div_scale_f32 v6, vcc, v5, v1, v5
	v_mul_f32_e32 v7, v6, v3
	v_fma_f32 v8, -v2, v7, v6
	v_fmac_f32_e32 v7, v8, v3
	v_fma_f32 v2, -v2, v7, v6
	v_div_fmas_f32 v2, v2, v3, v7
	v_div_fixup_f32 v1, v2, v1, v5
	v_div_scale_f32 v2, s[2:3], v0, v0, v4
	v_rcp_f32_e32 v3, v2
	s_nop 0
	v_fma_f32 v5, -v2, v3, 1.0
	v_fmac_f32_e32 v3, v5, v3
	v_div_scale_f32 v5, vcc, v4, v0, v4
	v_mul_f32_e32 v6, v5, v3
	v_fma_f32 v7, -v2, v6, v5
	v_fmac_f32_e32 v6, v7, v3
	v_fma_f32 v2, -v2, v6, v5
	v_div_fmas_f32 v2, v2, v3, v6
	v_div_fixup_f32 v0, v2, v0, v4
	v_add_u32_e32 v2, 0x8918, v12
	v_cmp_gt_i32_e32 vcc, 64, v80
	ds_write2_b32 v2, v0, v1 offset1:1
	s_and_saveexec_b64 s[2:3], vcc
	s_cbranch_execz .LBB0_364
	s_ashr_i32 s4, s28, 5
	s_add_i32 s4, s4, s29
	s_mul_i32 s22, s22, -6
	s_ashr_i32 s5, s4, 31
	s_add_i32 s22, s54, s22
	s_ashr_i32 s6, s23, 31
	s_lshl_b64 s[4:5], s[4:5], 11
	s_add_u32 s4, s23, s4
	v_ashrrev_i32_e32 v81, 31, v80
	s_addc_u32 s5, s6, s5
	v_lshl_add_u64 v[0:1], s[4:5], 0, v[80:81]
	v_readlane_b32 s4, v252, 0
	v_readlane_b32 s5, v252, 1
	s_movk_i32 s6, 0xa00
	s_ashr_i32 s23, s22, 31
	v_mov_b64_e32 v[2:3], s[4:5]
	v_mad_u64_u32 v[2:3], s[4:5], v0, s6, v[2:3]
	v_mad_i32_i24 v3, v1, s6, v3
	v_lshl_add_u64 v[0:1], s[22:23], 1, v[2:3]
	global_load_ushort v2, v[0:1], off offset:2304
	global_load_ushort v206, v[0:1], off offset:2316
	global_load_ushort v207, v[0:1], off offset:2328
	global_load_ushort v208, v[0:1], off offset:2340
	s_lshl_b32 s34, s22, 2
	v_mov_b32_e32 v210, s34
	global_load_dword v209, v210, s[48:49]
	global_load_dword v211, v210, s[50:51]
	global_load_dword v212, v210, s[48:49] offset:24
	global_load_dword v213, v210, s[50:51] offset:24
	s_mov_b32 s9, 0xbfb8aa3b
	s_mov_b32 s10, 0x3f2aaaab
	s_mov_b32 s11, 0x3f317218
	s_mov_b32 s8, 0x7f800000
	s_mov_b32 s12, 0x33800000
	s_waitcnt vmcnt(0)
	v_lshlrev_b32_e32 v2, 16, v2
	v_mul_f32_e32 v2, 0xbfb8aa3b, v2
	v_exp_f32_e32 v2, v2
	s_nop 0
	v_add_f32_e32 v2, 1.0, v2
	v_div_scale_f32 v3, s[4:5], v2, v2, 1.0
	v_rcp_f32_e32 v4, v3
	s_nop 0
	v_fma_f32 v5, -v3, v4, 1.0
	v_fmac_f32_e32 v4, v5, v4
	v_div_scale_f32 v5, vcc, 1.0, v2, 1.0
	v_mul_f32_e32 v6, v5, v4
	v_fma_f32 v7, -v3, v6, v5
	v_fmac_f32_e32 v6, v7, v4
	v_fma_f32 v3, -v3, v6, v5
	v_div_fmas_f32 v3, v3, v4, v6
	v_mov_b32_e32 v4, v206
	v_div_fixup_f32 v3, v3, v2, 1.0
	v_lshl_add_u32 v2, v80, 2, 0
	v_add_u32_e32 v2, 0x21a00, v2
	s_waitcnt vmcnt(0)
	v_lshlrev_b32_e32 v4, 16, v4
	v_mul_f32_e32 v4, 0xbfb8aa3b, v4
	v_exp_f32_e32 v4, v4
	s_nop 0
	v_add_f32_e32 v4, 1.0, v4
	v_div_scale_f32 v5, s[4:5], v4, v4, 1.0
	v_rcp_f32_e32 v6, v5
	s_lshl_b64 s[4:5], s[22:23], 2
	s_add_u32 s6, s48, s4
	s_addc_u32 s7, s49, s5
	v_fma_f32 v7, -v5, v6, 1.0
	v_fmac_f32_e32 v6, v7, v6
	v_div_scale_f32 v7, vcc, 1.0, v4, 1.0
	v_mul_f32_e32 v8, v7, v6
	v_fma_f32 v9, -v5, v8, v7
	v_fmac_f32_e32 v8, v9, v6
	v_fma_f32 v5, -v5, v8, v7
	v_div_fmas_f32 v5, v5, v6, v8
	v_div_fixup_f32 v4, v5, v4, 1.0
	s_add_u32 s4, s50, s4
	ds_write2st64_b32 v2, v3, v4 offset0:2 offset1:3
	v_mov_b32_e32 v4, v207
	s_addc_u32 s5, s51, s5
	v_mov_b32_e32 v3, v209
	v_mov_b32_e32 v5, v211
	s_add_i32 s34, s22, 6
	s_lshl_b64 s[4:5], s[34:35], 2
	s_add_u32 s6, s48, s4
	s_addc_u32 s7, s49, s5
	s_add_u32 s4, s50, s4
	v_mov_b32_e32 v0, v208
	s_addc_u32 s5, s51, s5
	v_mov_b32_e32 v1, v213
	s_waitcnt vmcnt(4)
	v_lshlrev_b32_e32 v4, 16, v4
	s_waitcnt vmcnt(3)
	v_mul_f32_e32 v3, 0x3fb8aa3b, v3
	s_waitcnt vmcnt(2)
	v_add_f32_e32 v4, v5, v4
	v_max_f32_e32 v6, 0, v4
	v_mul_f32_e64 v4, |v4|, s9
	v_exp_f32_e32 v7, v4
	v_exp_f32_e32 v3, v3
	s_waitcnt vmcnt(1)
	v_lshlrev_b32_e32 v0, 16, v0
	v_add_f32_e32 v8, 1.0, v7
	v_add_f32_e32 v4, -1.0, v8
	v_sub_f32_e32 v5, v4, v8
	v_add_f32_e32 v5, 1.0, v5
	v_sub_f32_e32 v4, v7, v4
	v_add_f32_e32 v9, v4, v5
	v_frexp_mant_f32_e32 v4, v8
	v_cmp_gt_f32_e32 vcc, s10, v4
	v_cvt_f64_f32_e32 v[4:5], v8
	v_frexp_exp_i32_f64_e32 v4, v[4:5]
	v_subbrev_co_u32_e32 v4, vcc, 0, v4, vcc
	v_sub_u32_e32 v5, 0, v4
	v_ldexp_f32 v8, v8, v5
	v_ldexp_f32 v5, v9, v5
	v_add_f32_e32 v9, -1.0, v8
	v_add_f32_e32 v10, 1.0, v9
	v_sub_f32_e32 v10, v8, v10
	v_add_f32_e32 v10, v5, v10
	v_add_f32_e32 v11, v9, v10
	v_sub_f32_e32 v9, v11, v9
	v_sub_f32_e32 v9, v10, v9
	v_add_f32_e32 v10, 1.0, v8
	v_add_f32_e32 v12, -1.0, v10
	v_sub_f32_e32 v8, v8, v12
	v_add_f32_e32 v5, v5, v8
	v_add_f32_e32 v8, v10, v5
	v_sub_f32_e32 v10, v8, v10
	v_sub_f32_e32 v5, v5, v10
	v_rcp_f32_e32 v10, v8
	v_cvt_f32_i32_e32 v4, v4
	v_cmp_neq_f32_e32 vcc, s8, v7
	s_waitcnt vmcnt(0)
	v_add_f32_e32 v0, v1, v0
	v_mul_f32_e32 v12, v11, v10
	v_mul_f32_e32 v13, v8, v12
	v_fma_f32 v14, v12, v8, -v13
	v_fmac_f32_e32 v14, v12, v5
	v_add_f32_e32 v15, v13, v14
	v_sub_f32_e32 v52, v11, v15
	v_sub_f32_e32 v11, v11, v52
	v_sub_f32_e32 v13, v15, v13
	v_sub_f32_e32 v11, v11, v15
	v_add_f32_e32 v9, v9, v11
	v_sub_f32_e32 v11, v13, v14
	v_add_f32_e32 v9, v11, v9
	v_add_f32_e32 v11, v52, v9
	v_mul_f32_e32 v13, v10, v11
	v_mul_f32_e32 v14, v8, v13
	v_fma_f32 v8, v13, v8, -v14
	v_fmac_f32_e32 v8, v13, v5
	v_sub_f32_e32 v5, v52, v11
	v_add_f32_e32 v5, v9, v5
	v_add_f32_e32 v9, v14, v8
	v_sub_f32_e32 v15, v11, v9
	v_sub_f32_e32 v11, v11, v15
	v_sub_f32_e32 v14, v9, v14
	v_sub_f32_e32 v9, v11, v9
	v_add_f32_e32 v5, v5, v9
	v_sub_f32_e32 v8, v14, v8
	v_add_f32_e32 v5, v8, v5
	v_add_f32_e32 v8, v12, v13
	v_add_f32_e32 v5, v15, v5
	v_sub_f32_e32 v9, v8, v12
	v_mul_f32_e32 v5, v10, v5
	v_sub_f32_e32 v9, v13, v9
	v_add_f32_e32 v5, v9, v5
	v_mul_f32_e32 v12, 0x3f317218, v4
	v_add_f32_e32 v9, v8, v5
	v_fma_f32 v13, v4, s11, -v12
	v_mul_f32_e32 v10, v9, v9
	v_fmac_f32_e32 v13, 0xb102e308, v4
	v_sub_f32_e32 v4, v9, v8
	v_fmamk_f32 v11, v10, 0x3e9b6dac, v237
	v_sub_f32_e32 v4, v5, v4
	v_add_f32_e32 v5, v12, v13
	v_fmaak_f32 v11, v10, v11, 0x3f2aaada
	v_sub_f32_e32 v8, v5, v12
	v_ldexp_f32 v12, v9, 1
	v_mul_f32_e32 v9, v9, v10
	v_mul_f32_e32 v9, v9, v11
	v_add_f32_e32 v10, v12, v9
	v_sub_f32_e32 v11, v10, v12
	v_ldexp_f32 v4, v4, 1
	v_sub_f32_e32 v9, v9, v11
	v_add_f32_e32 v4, v4, v9
	v_add_f32_e32 v9, v10, v4
	v_sub_f32_e32 v10, v9, v10
	v_sub_f32_e32 v4, v4, v10
	v_add_f32_e32 v10, v5, v9
	v_sub_f32_e32 v11, v10, v5
	v_sub_f32_e32 v12, v10, v11
	v_sub_f32_e32 v8, v13, v8
	v_sub_f32_e32 v5, v5, v12
	v_sub_f32_e32 v9, v9, v11
	v_add_f32_e32 v5, v9, v5
	v_add_f32_e32 v9, v8, v4
	v_sub_f32_e32 v11, v9, v8
	v_sub_f32_e32 v12, v9, v11
	v_sub_f32_e32 v8, v8, v12
	v_sub_f32_e32 v4, v4, v11
	v_add_f32_e32 v5, v9, v5
	v_add_f32_e32 v4, v4, v8
	v_add_f32_e32 v8, v10, v5
	v_sub_f32_e32 v9, v8, v10
	v_sub_f32_e32 v5, v5, v9
	v_add_f32_e32 v4, v4, v5
	v_add_f32_e32 v4, v8, v4
	v_cndmask_b32_e32 v4, v239, v4, vcc
	v_cmp_ngt_f32_e32 vcc, -1.0, v7
	v_max_f32_e32 v5, 0, v0
	v_mul_f32_e64 v0, |v0|, s9
	v_cndmask_b32_e32 v4, v238, v4, vcc
	v_cmp_neq_f32_e32 vcc, -1.0, v7
	s_nop 1
	v_cndmask_b32_e32 v4, v243, v4, vcc
	v_cmp_lt_f32_e64 vcc, |v7|, s12
	s_nop 1
	v_cndmask_b32_e32 v4, v4, v7, vcc
	v_add_f32_e32 v4, v6, v4
	v_mul_f32_e64 v3, v4, -v3
	v_mov_b32_e32 v4, v212
	v_exp_f32_e32 v6, v0
	s_waitcnt vmcnt(0)
	v_mul_f32_e32 v4, 0x3fb8aa3b, v4
	v_add_f32_e32 v7, 1.0, v6
	v_add_f32_e32 v0, -1.0, v7
	v_sub_f32_e32 v1, v0, v7
	v_add_f32_e32 v1, 1.0, v1
	v_sub_f32_e32 v0, v6, v0
	v_add_f32_e32 v8, v0, v1
	v_frexp_mant_f32_e32 v0, v7
	v_cmp_gt_f32_e32 vcc, s10, v0
	v_cvt_f64_f32_e32 v[0:1], v7
	v_frexp_exp_i32_f64_e32 v0, v[0:1]
	v_subbrev_co_u32_e32 v0, vcc, 0, v0, vcc
	v_sub_u32_e32 v1, 0, v0
	v_ldexp_f32 v7, v7, v1
	v_ldexp_f32 v1, v8, v1
	v_add_f32_e32 v8, -1.0, v7
	v_add_f32_e32 v9, 1.0, v8
	v_sub_f32_e32 v9, v7, v9
	v_add_f32_e32 v9, v1, v9
	v_add_f32_e32 v10, v8, v9
	v_sub_f32_e32 v8, v10, v8
	v_sub_f32_e32 v8, v9, v8
	v_add_f32_e32 v9, 1.0, v7
	v_add_f32_e32 v11, -1.0, v9
	v_sub_f32_e32 v7, v7, v11
	v_add_f32_e32 v1, v1, v7
	v_add_f32_e32 v7, v9, v1
	v_sub_f32_e32 v9, v7, v9
	v_sub_f32_e32 v1, v1, v9
	v_rcp_f32_e32 v9, v7
	v_cvt_f32_i32_e32 v0, v0
	v_cmp_neq_f32_e32 vcc, s8, v6
	v_exp_f32_e32 v4, v4
	v_mul_f32_e32 v11, v10, v9
	v_mul_f32_e32 v12, v7, v11
	v_fma_f32 v13, v11, v7, -v12
	v_fmac_f32_e32 v13, v11, v1
	v_add_f32_e32 v14, v12, v13
	v_sub_f32_e32 v15, v10, v14
	v_sub_f32_e32 v10, v10, v15
	v_sub_f32_e32 v12, v14, v12
	v_sub_f32_e32 v10, v10, v14
	v_add_f32_e32 v8, v8, v10
	v_sub_f32_e32 v10, v12, v13
	v_add_f32_e32 v8, v10, v8
	v_add_f32_e32 v10, v15, v8
	v_mul_f32_e32 v12, v9, v10
	v_mul_f32_e32 v13, v7, v12
	v_fma_f32 v7, v12, v7, -v13
	v_fmac_f32_e32 v7, v12, v1
	v_sub_f32_e32 v1, v15, v10
	v_add_f32_e32 v1, v8, v1
	v_add_f32_e32 v8, v13, v7
	v_sub_f32_e32 v14, v10, v8
	v_sub_f32_e32 v10, v10, v14
	v_sub_f32_e32 v13, v8, v13
	v_sub_f32_e32 v8, v10, v8
	v_add_f32_e32 v1, v1, v8
	v_sub_f32_e32 v7, v13, v7
	v_add_f32_e32 v1, v7, v1
	v_add_f32_e32 v7, v11, v12
	v_add_f32_e32 v1, v14, v1
	v_sub_f32_e32 v8, v7, v11
	v_mul_f32_e32 v1, v9, v1
	v_sub_f32_e32 v8, v12, v8
	v_add_f32_e32 v1, v8, v1
	v_mul_f32_e32 v11, 0x3f317218, v0
	v_add_f32_e32 v8, v7, v1
	v_fma_f32 v12, v0, s11, -v11
	v_mul_f32_e32 v9, v8, v8
	v_fmac_f32_e32 v12, 0xb102e308, v0
	v_sub_f32_e32 v0, v8, v7
	v_fmamk_f32 v10, v9, 0x3e9b6dac, v237
	v_sub_f32_e32 v0, v1, v0
	v_add_f32_e32 v1, v11, v12
	v_fmaak_f32 v10, v9, v10, 0x3f2aaada
	v_sub_f32_e32 v7, v1, v11
	v_ldexp_f32 v11, v8, 1
	v_mul_f32_e32 v8, v8, v9
	v_mul_f32_e32 v8, v8, v10
	v_add_f32_e32 v9, v11, v8
	v_sub_f32_e32 v10, v9, v11
	v_ldexp_f32 v0, v0, 1
	v_sub_f32_e32 v8, v8, v10
	v_add_f32_e32 v0, v0, v8
	v_add_f32_e32 v8, v9, v0
	v_sub_f32_e32 v9, v8, v9
	v_sub_f32_e32 v0, v0, v9
	v_add_f32_e32 v9, v1, v8
	v_sub_f32_e32 v10, v9, v1
	v_sub_f32_e32 v11, v9, v10
	v_sub_f32_e32 v7, v12, v7
	v_sub_f32_e32 v1, v1, v11
	v_sub_f32_e32 v8, v8, v10
	v_add_f32_e32 v1, v8, v1
	v_add_f32_e32 v8, v7, v0
	v_sub_f32_e32 v10, v8, v7
	v_sub_f32_e32 v11, v8, v10
	v_sub_f32_e32 v7, v7, v11
	v_sub_f32_e32 v0, v0, v10
	v_add_f32_e32 v1, v8, v1
	v_add_f32_e32 v0, v0, v7
	v_add_f32_e32 v7, v9, v1
	v_sub_f32_e32 v8, v7, v9
	v_sub_f32_e32 v1, v1, v8
	v_add_f32_e32 v0, v0, v1
	v_add_f32_e32 v0, v7, v0
	v_cndmask_b32_e32 v0, v239, v0, vcc
	v_cmp_ngt_f32_e32 vcc, -1.0, v6
	s_nop 1
	v_cndmask_b32_e32 v0, v238, v0, vcc
	v_cmp_neq_f32_e32 vcc, -1.0, v6
	s_nop 1
	v_cndmask_b32_e32 v0, v243, v0, vcc
	v_cmp_lt_f32_e64 vcc, |v6|, s12
	s_nop 1
	v_cndmask_b32_e32 v0, v0, v6, vcc
	v_add_f32_e32 v0, v5, v0
	v_mul_f32_e64 v0, v0, -v4
	ds_write2st64_b32 v2, v3, v0 offset1:1
